# weight-conversion hook in the attention phase prefetches three tiles ahead (third register set) instead of two
# baseline (speedup 1.0000x reference)
; __device__ __forceinline__ u16 f2bf(float f) { return (u16)(pack2(f, 0.f) & 0xffffu); }
; __device__ __forceinline__ int tid_() { int t = threadIdx.x; asm volatile("" : "+v"(t)); return t; }
; __device__ __forceinline__ void convT_tile(const float* __restrict__ src, int lds, int k0, int c0, u16* __restrict__ dst, int Kd,
;                                            int rbase, int mode, int which, unsigned char* smem, const float* __restrict__ kscale = nullptr) {
;   float* tile = (float*)smem;
;   const int t = tid_();
;   float4 v4[4];
; #pragma unroll
;   for (int i = 0; i < 4; ++i) {
;     const f32x4 w_ = __builtin_nontemporal_load((const f32x4*)(src + (size_t)(k0 + i * 16 + (t >> 4)) * lds + c0 + (t & 15) * 4));
;     v4[i] = make_float4(w_[0], w_[1], w_[2], w_[3]);
;   }
; #pragma unroll
;   for (int i = 0; i < 4; ++i) {
;     const int kk = i * 16 + (t >> 4), cc = (t & 15) * 4;
;     const float sc = kscale ? kscale[k0 + kk] : 1.f;
;     tile[kk * 65 + cc + 0] = v4[i].x * sc; tile[kk * 65 + cc + 1] = v4[i].y * sc;
;     tile[kk * 65 + cc + 2] = v4[i].z * sc; tile[kk * 65 + cc + 3] = v4[i].w * sc;
;   }
;   __syncthreads();
; #pragma unroll
;   for (int i = 0; i < 16; ++i) {
;     const int cc = i * 4 + (t >> 6), kk = t & 63;
;     int row;
;     if (mode == 0) row = rbase + cc;
;     else { const int f = c0 + cc; row = (((f >> 4) * 2 + which) << 4) + (f & 15); }
;     dst[(size_t)row * Kd + k0 + kk] = f2bf(tile[kk * 65 + cc]);
;   }
;   __syncthreads();
; }
; __device__ __forceinline__ void conv_item(const Params& p, int it, unsigned char* smem) {
;     ...
;   if (r < 4096) {
;     const int which = r >> 11, r2 = r & 2047, e = r2 >> 7, r3 = r2 & 127, ct = r3 >> 4, kt = r3 & 15;
;     const float* src = (which ? p.w_up : p.w_gate) + (size_t)(l * 16 + e) * 1024 * 512;
;     convT_tile(src, 512, kt * 64, ct * 64, p.WguT + (size_t)(l * 16 + e) * 1024 * 1024, 1024, 0, 1, which, smem);
;     return;
.Lcv_se1:
	v_lshl_add_u32 v116, v98, s94, v102
	v_lshl_add_u32 v117, v99, s94, v102
	v_lshl_add_u32 v118, v100, s94, v102
	v_lshl_add_u32 v119, v101, s94, v102
	global_load_dwordx4 v[148:151], v116, s[88:89] nt
	global_load_dwordx4 v[152:155], v117, s[88:89] nt
	global_load_dwordx4 v[156:159], v118, s[88:89] nt
	global_load_dwordx4 v[160:163], v119, s[88:89] nt
	s_add_i32 s59, s2, 0x400
	s_cmp_lt_u32 s59, 0x1000
	s_cbranch_scc0 .Lcv_sd2
	s_lshr_b32 s60, s59, 11
	s_bfe_u32 s71, s59, 0x40007
	s_bfe_u32 s35, s59, 0x30004
	s_and_b32 s51, s59, 15
	s_lshl_b32 s0, s36, 4
	s_add_i32 s71, s71, s0
	s_lshl_b32 s71, s71, 21
	s_lshl_b32 s0, s51, 17
	s_add_i32 s71, s71, s0
	s_lshl_b32 s0, s35, 8
	s_add_i32 s71, s71, s0
	s_cmp_eq_u32 s60, 0
	s_cselect_b32 s88, s52, s54
	s_cselect_b32 s89, s53, s55
	s_add_u32 s88, s88, s71
	s_addc_u32 s89, s89, 0
	s_mov_b32 s94, 11
	s_branch .Lcv_se2

; __device__ __forceinline__ u16 f2bf(float f) { return (u16)(pack2(f, 0.f) & 0xffffu); }
; __device__ __forceinline__ int tid_() { int t = threadIdx.x; asm volatile("" : "+v"(t)); return t; }
; __device__ __forceinline__ void convT_tile(const float* __restrict__ src, int lds, int k0, int c0, u16* __restrict__ dst, int Kd,
;                                            int rbase, int mode, int which, unsigned char* smem, const float* __restrict__ kscale = nullptr) {
;   float* tile = (float*)smem;
;   const int t = tid_();
;   float4 v4[4];
; #pragma unroll
;   for (int i = 0; i < 4; ++i) {
;     const f32x4 w_ = __builtin_nontemporal_load((const f32x4*)(src + (size_t)(k0 + i * 16 + (t >> 4)) * lds + c0 + (t & 15) * 4));
;     v4[i] = make_float4(w_[0], w_[1], w_[2], w_[3]);
;   }
; #pragma unroll
;   for (int i = 0; i < 4; ++i) {
;     const int kk = i * 16 + (t >> 4), cc = (t & 15) * 4;
;     const float sc = kscale ? kscale[k0 + kk] : 1.f;
;     tile[kk * 65 + cc + 0] = v4[i].x * sc; tile[kk * 65 + cc + 1] = v4[i].y * sc;
;     tile[kk * 65 + cc + 2] = v4[i].z * sc; tile[kk * 65 + cc + 3] = v4[i].w * sc;
;   }
;   __syncthreads();
; #pragma unroll
;   for (int i = 0; i < 16; ++i) {
;     const int cc = i * 4 + (t >> 6), kk = t & 63;
;     int row;
;     if (mode == 0) row = rbase + cc;
;     else { const int f = c0 + cc; row = (((f >> 4) * 2 + which) << 4) + (f & 15); }
;     dst[(size_t)row * Kd + k0 + kk] = f2bf(tile[kk * 65 + cc]);
;   }
;   __syncthreads();
; }
; __device__ __forceinline__ void conv_item(const Params& p, int it, unsigned char* smem) {
;     ...
;   if (r < 4096) {
;     const int which = r >> 11, r2 = r & 2047, e = r2 >> 7, r3 = r2 & 127, ct = r3 >> 4, kt = r3 & 15;
;     const float* src = (which ? p.w_up : p.w_gate) + (size_t)(l * 16 + e) * 1024 * 512;
;     convT_tile(src, 512, kt * 64, ct * 64, p.WguT + (size_t)(l * 16 + e) * 1024 * 1024, 1024, 0, 1, which, smem);
;     return;
.Lcv_se2:
	v_lshl_add_u32 v116, v98, s94, v102
	v_lshl_add_u32 v117, v99, s94, v102
	v_lshl_add_u32 v118, v100, s94, v102
	v_lshl_add_u32 v119, v101, s94, v102
	global_load_dwordx4 v[54:57], v116, s[88:89] nt
	global_load_dwordx4 v[58:61], v117, s[88:89] nt
	global_load_dwordx4 v[62:65], v118, s[88:89] nt
	global_load_dwordx4 v[66:69], v119, s[88:89] nt
	s_add_i32 s59, s2, 0x0
	s_cmp_lt_u32 s59, 0x1000
	s_cbranch_scc0 .Lcv_dd0
	s_lshr_b32 s60, s59, 11
	s_bfe_u32 s71, s59, 0x40007
	s_bfe_u32 s35, s59, 0x30004
	s_and_b32 s51, s59, 15
	s_lshl_b32 s0, s36, 4
	s_add_i32 s71, s71, s0
	s_lshl_b32 s71, s71, 21
	s_lshl_b32 s35, s35, 7
	s_lshl_b32 s60, s60, 4
	s_add_i32 s35, s35, s60
	s_lshl_b32 s35, s35, 11
	s_add_i32 s71, s71, s35
	s_lshl_b32 s51, s51, 7
	s_add_i32 s71, s71, s51
	s_add_u32 s0, s98, s71
	s_addc_u32 s1, s99, 0
	v_mov_b32_e32 v120, v103
	v_mov_b32_e32 v121, v104
	s_branch .Lcv_de0

; __device__ __forceinline__ u16 f2bf(float f) { return (u16)(pack2(f, 0.f) & 0xffffu); }
; __device__ __forceinline__ void convT_tile(const float* __restrict__ src, int lds, int k0, int c0, u16* __restrict__ dst, int Kd,
;                                            int rbase, int mode, int which, unsigned char* smem, const float* __restrict__ kscale = nullptr) {
;     ...
; #pragma unroll
;   for (int i = 0; i < 4; ++i) {
;     const int kk = i * 16 + (t >> 4), cc = (t & 15) * 4;
;     const float sc = kscale ? kscale[k0 + kk] : 1.f;
;     tile[kk * 65 + cc + 0] = v4[i].x * sc; tile[kk * 65 + cc + 1] = v4[i].y * sc;
;     tile[kk * 65 + cc + 2] = v4[i].z * sc; tile[kk * 65 + cc + 3] = v4[i].w * sc;
;   }
;   __syncthreads();
; #pragma unroll
;   for (int i = 0; i < 16; ++i) {
;     const int cc = i * 4 + (t >> 6), kk = t & 63;
;     int row;
;     if (mode == 0) row = rbase + cc;
;     else { const int f = c0 + cc; row = (((f >> 4) * 2 + which) << 4) + (f & 15); }
;     dst[(size_t)row * Kd + k0 + kk] = f2bf(tile[kk * 65 + cc]);
;   }
;   __syncthreads();
; }
.Lcv_de0:
	s_waitcnt vmcnt(8)
	ds_write2_b32 v107, v132, v133 offset1:1
	ds_write2_b32 v107, v134, v135 offset0:2 offset1:3
	ds_write2_b32 v108, v136, v137 offset1:1
	ds_write2_b32 v108, v138, v139 offset0:2 offset1:3
	ds_write2_b32 v109, v140, v141 offset1:1
	ds_write2_b32 v109, v142, v143 offset0:2 offset1:3
	ds_write2_b32 v110, v144, v145 offset1:1
	ds_write2_b32 v110, v146, v147 offset0:2 offset1:3
	s_waitcnt lgkmcnt(0)
	s_barrier
	ds_read_b32 v72, v115 offset:0
	ds_read_b32 v73, v115 offset:260
	ds_read_b32 v74, v115 offset:520
	ds_read_b32 v75, v115 offset:780
	ds_read_b32 v76, v115 offset:1040
	ds_read_b32 v77, v115 offset:1300
	ds_read_b32 v78, v115 offset:1560
	ds_read_b32 v79, v115 offset:1820
	ds_read_b32 v26, v115 offset:128
	ds_read_b32 v27, v115 offset:388
	ds_read_b32 v28, v115 offset:648
	ds_read_b32 v29, v115 offset:908
	ds_read_b32 v30, v115 offset:1168
	ds_read_b32 v31, v115 offset:1428
	ds_read_b32 v32, v115 offset:1688
	ds_read_b32 v33, v115 offset:1948
	s_waitcnt lgkmcnt(8)
	v_cvt_pk_bf16_f32 v124, v72, v73
	v_cvt_pk_bf16_f32 v125, v74, v75
	v_cvt_pk_bf16_f32 v126, v76, v77
	v_cvt_pk_bf16_f32 v127, v78, v79
	global_store_dwordx4 v120, v[124:127], s[0:1]
	s_waitcnt lgkmcnt(0)
	v_cvt_pk_bf16_f32 v128, v26, v27
	v_cvt_pk_bf16_f32 v129, v28, v29
	v_cvt_pk_bf16_f32 v130, v30, v31
	v_cvt_pk_bf16_f32 v131, v32, v33
	global_store_dwordx4 v121, v[128:131], s[0:1]
	s_add_i32 s59, s2, 0x600
	s_cmp_lt_u32 s59, 0x1000
	s_cbranch_scc0 .Lcv_sd3
	s_lshr_b32 s60, s59, 11
	s_bfe_u32 s71, s59, 0x40007
	s_bfe_u32 s35, s59, 0x30004
	s_and_b32 s51, s59, 15
	s_lshl_b32 s0, s36, 4
	s_add_i32 s71, s71, s0
	s_lshl_b32 s71, s71, 21
	s_lshl_b32 s0, s51, 17
	s_add_i32 s71, s71, s0
	s_lshl_b32 s0, s35, 8
	s_add_i32 s71, s71, s0
	s_cmp_eq_u32 s60, 0
	s_cselect_b32 s88, s52, s54
	s_cselect_b32 s89, s53, s55
	s_add_u32 s88, s88, s71
	s_addc_u32 s89, s89, 0
	s_mov_b32 s94, 11
	s_branch .Lcv_se3

; __device__ __forceinline__ u16 f2bf(float f) { return (u16)(pack2(f, 0.f) & 0xffffu); }
; __device__ __forceinline__ void convT_tile(const float* __restrict__ src, int lds, int k0, int c0, u16* __restrict__ dst, int Kd,
;                                            int rbase, int mode, int which, unsigned char* smem, const float* __restrict__ kscale = nullptr) {
;     ...
; #pragma unroll
;   for (int i = 0; i < 4; ++i) {
;     const int kk = i * 16 + (t >> 4), cc = (t & 15) * 4;
;     const float sc = kscale ? kscale[k0 + kk] : 1.f;
;     tile[kk * 65 + cc + 0] = v4[i].x * sc; tile[kk * 65 + cc + 1] = v4[i].y * sc;
;     tile[kk * 65 + cc + 2] = v4[i].z * sc; tile[kk * 65 + cc + 3] = v4[i].w * sc;
;   }
;   __syncthreads();
; #pragma unroll
;   for (int i = 0; i < 16; ++i) {
;     const int cc = i * 4 + (t >> 6), kk = t & 63;
;     int row;
;     if (mode == 0) row = rbase + cc;
;     else { const int f = c0 + cc; row = (((f >> 4) * 2 + which) << 4) + (f & 15); }
;     dst[(size_t)row * Kd + k0 + kk] = f2bf(tile[kk * 65 + cc]);
;   }
;   __syncthreads();
; }
.Lcv_de1:
	s_waitcnt vmcnt(10)
	ds_write2_b32 v111, v148, v149 offset1:1
	ds_write2_b32 v111, v150, v151 offset0:2 offset1:3
	ds_write2_b32 v112, v152, v153 offset1:1
	ds_write2_b32 v112, v154, v155 offset0:2 offset1:3
	ds_write2_b32 v113, v156, v157 offset1:1
	ds_write2_b32 v113, v158, v159 offset0:2 offset1:3
	ds_write2_b32 v114, v160, v161 offset1:1
	ds_write2_b32 v114, v162, v163 offset0:2 offset1:3
	s_waitcnt lgkmcnt(0)
	s_barrier
	ds_read_b32 v72, v115 offset:16640
	ds_read_b32 v73, v115 offset:16900
	ds_read_b32 v74, v115 offset:17160
	ds_read_b32 v75, v115 offset:17420
	ds_read_b32 v76, v115 offset:17680
	ds_read_b32 v77, v115 offset:17940
	ds_read_b32 v78, v115 offset:18200
	ds_read_b32 v79, v115 offset:18460
	ds_read_b32 v26, v115 offset:16768
	ds_read_b32 v27, v115 offset:17028
	ds_read_b32 v28, v115 offset:17288
	ds_read_b32 v29, v115 offset:17548
	ds_read_b32 v30, v115 offset:17808
	ds_read_b32 v31, v115 offset:18068
	ds_read_b32 v32, v115 offset:18328
	ds_read_b32 v33, v115 offset:18588
	s_waitcnt lgkmcnt(8)
	v_cvt_pk_bf16_f32 v124, v72, v73
	v_cvt_pk_bf16_f32 v125, v74, v75
	v_cvt_pk_bf16_f32 v126, v76, v77
	v_cvt_pk_bf16_f32 v127, v78, v79
	global_store_dwordx4 v120, v[124:127], s[0:1]
	s_waitcnt lgkmcnt(0)
	v_cvt_pk_bf16_f32 v128, v26, v27
	v_cvt_pk_bf16_f32 v129, v28, v29
	v_cvt_pk_bf16_f32 v130, v30, v31
	v_cvt_pk_bf16_f32 v131, v32, v33
	global_store_dwordx4 v121, v[128:131], s[0:1]
	s_add_i32 s59, s2, 0x800
	s_cmp_lt_u32 s59, 0x1000
	s_cbranch_scc0 .Lcv_sd4
	s_lshr_b32 s60, s59, 11
	s_bfe_u32 s71, s59, 0x40007
	s_bfe_u32 s35, s59, 0x30004
	s_and_b32 s51, s59, 15
	s_lshl_b32 s0, s36, 4
	s_add_i32 s71, s71, s0
	s_lshl_b32 s71, s71, 21
	s_lshl_b32 s0, s51, 17
	s_add_i32 s71, s71, s0
	s_lshl_b32 s0, s35, 8
	s_add_i32 s71, s71, s0
	s_cmp_eq_u32 s60, 0
	s_cselect_b32 s88, s52, s54
	s_cselect_b32 s89, s53, s55
	s_add_u32 s88, s88, s71
	s_addc_u32 s89, s89, 0
	s_mov_b32 s94, 11
	s_branch .Lcv_se4

; __device__ __forceinline__ u16 f2bf(float f) { return (u16)(pack2(f, 0.f) & 0xffffu); }
; __device__ __forceinline__ void convT_tile(const float* __restrict__ src, int lds, int k0, int c0, u16* __restrict__ dst, int Kd,
;                                            int rbase, int mode, int which, unsigned char* smem, const float* __restrict__ kscale = nullptr) {
;     ...
; #pragma unroll
;   for (int i = 0; i < 4; ++i) {
;     const int kk = i * 16 + (t >> 4), cc = (t & 15) * 4;
;     const float sc = kscale ? kscale[k0 + kk] : 1.f;
;     tile[kk * 65 + cc + 0] = v4[i].x * sc; tile[kk * 65 + cc + 1] = v4[i].y * sc;
;     tile[kk * 65 + cc + 2] = v4[i].z * sc; tile[kk * 65 + cc + 3] = v4[i].w * sc;
;   }
;   __syncthreads();
; #pragma unroll
;   for (int i = 0; i < 16; ++i) {
;     const int cc = i * 4 + (t >> 6), kk = t & 63;
;     int row;
;     if (mode == 0) row = rbase + cc;
;     else { const int f = c0 + cc; row = (((f >> 4) * 2 + which) << 4) + (f & 15); }
;     dst[(size_t)row * Kd + k0 + kk] = f2bf(tile[kk * 65 + cc]);
;   }
;   __syncthreads();
; }
.Lcv_de2:
	s_waitcnt vmcnt(12)
	ds_write2_b32 v107, v54, v55 offset1:1
	ds_write2_b32 v107, v56, v57 offset0:2 offset1:3
	ds_write2_b32 v108, v58, v59 offset1:1
	ds_write2_b32 v108, v60, v61 offset0:2 offset1:3
	ds_write2_b32 v109, v62, v63 offset1:1
	ds_write2_b32 v109, v64, v65 offset0:2 offset1:3
	ds_write2_b32 v110, v66, v67 offset1:1
	ds_write2_b32 v110, v68, v69 offset0:2 offset1:3
	s_waitcnt lgkmcnt(0)
	s_barrier
	ds_read_b32 v72, v115 offset:0
	ds_read_b32 v73, v115 offset:260
	ds_read_b32 v74, v115 offset:520
	ds_read_b32 v75, v115 offset:780
	ds_read_b32 v76, v115 offset:1040
	ds_read_b32 v77, v115 offset:1300
	ds_read_b32 v78, v115 offset:1560
	ds_read_b32 v79, v115 offset:1820
	ds_read_b32 v26, v115 offset:128
	ds_read_b32 v27, v115 offset:388
	ds_read_b32 v28, v115 offset:648
	ds_read_b32 v29, v115 offset:908
	ds_read_b32 v30, v115 offset:1168
	ds_read_b32 v31, v115 offset:1428
	ds_read_b32 v32, v115 offset:1688
	ds_read_b32 v33, v115 offset:1948
	s_waitcnt lgkmcnt(8)
	v_cvt_pk_bf16_f32 v124, v72, v73
	v_cvt_pk_bf16_f32 v125, v74, v75
	v_cvt_pk_bf16_f32 v126, v76, v77
	v_cvt_pk_bf16_f32 v127, v78, v79
	global_store_dwordx4 v120, v[124:127], s[0:1]
	s_waitcnt lgkmcnt(0)
	v_cvt_pk_bf16_f32 v128, v26, v27
	v_cvt_pk_bf16_f32 v129, v28, v29
	v_cvt_pk_bf16_f32 v130, v30, v31
	v_cvt_pk_bf16_f32 v131, v32, v33
	global_store_dwordx4 v121, v[128:131], s[0:1]
	s_add_i32 s59, s2, 0xa00
	s_cmp_lt_u32 s59, 0x1000
	s_cbranch_scc0 .Lcv_sd5
	s_lshr_b32 s60, s59, 11
	s_bfe_u32 s71, s59, 0x40007
	s_bfe_u32 s35, s59, 0x30004
	s_and_b32 s51, s59, 15
	s_lshl_b32 s0, s36, 4
	s_add_i32 s71, s71, s0
	s_lshl_b32 s71, s71, 21
	s_lshl_b32 s0, s51, 17
	s_add_i32 s71, s71, s0
	s_lshl_b32 s0, s35, 8
	s_add_i32 s71, s71, s0
	s_cmp_eq_u32 s60, 0
	s_cselect_b32 s88, s52, s54
	s_cselect_b32 s89, s53, s55
	s_add_u32 s88, s88, s71
	s_addc_u32 s89, s89, 0
	s_mov_b32 s94, 11
	s_branch .Lcv_se5

; __device__ __forceinline__ u16 f2bf(float f) { return (u16)(pack2(f, 0.f) & 0xffffu); }
; __device__ __forceinline__ int tid_() { int t = threadIdx.x; asm volatile("" : "+v"(t)); return t; }
; __device__ __forceinline__ void convT_tile(const float* __restrict__ src, int lds, int k0, int c0, u16* __restrict__ dst, int Kd,
;                                            int rbase, int mode, int which, unsigned char* smem, const float* __restrict__ kscale = nullptr) {
;   float* tile = (float*)smem;
;   const int t = tid_();
;   float4 v4[4];
; #pragma unroll
;   for (int i = 0; i < 4; ++i) {
;     const f32x4 w_ = __builtin_nontemporal_load((const f32x4*)(src + (size_t)(k0 + i * 16 + (t >> 4)) * lds + c0 + (t & 15) * 4));
;     v4[i] = make_float4(w_[0], w_[1], w_[2], w_[3]);
;   }
; #pragma unroll
;   for (int i = 0; i < 4; ++i) {
;     const int kk = i * 16 + (t >> 4), cc = (t & 15) * 4;
;     const float sc = kscale ? kscale[k0 + kk] : 1.f;
;     tile[kk * 65 + cc + 0] = v4[i].x * sc; tile[kk * 65 + cc + 1] = v4[i].y * sc;
;     tile[kk * 65 + cc + 2] = v4[i].z * sc; tile[kk * 65 + cc + 3] = v4[i].w * sc;
;   }
;   __syncthreads();
; #pragma unroll
;   for (int i = 0; i < 16; ++i) {
;     const int cc = i * 4 + (t >> 6), kk = t & 63;
;     int row;
;     if (mode == 0) row = rbase + cc;
;     else { const int f = c0 + cc; row = (((f >> 4) * 2 + which) << 4) + (f & 15); }
;     dst[(size_t)row * Kd + k0 + kk] = f2bf(tile[kk * 65 + cc]);
;   }
;   __syncthreads();
; }
; __device__ __forceinline__ void conv_item(const Params& p, int it, unsigned char* smem) {
;     ...
;   if (r < 4096) {
;     const int which = r >> 11, r2 = r & 2047, e = r2 >> 7, r3 = r2 & 127, ct = r3 >> 4, kt = r3 & 15;
;     const float* src = (which ? p.w_up : p.w_gate) + (size_t)(l * 16 + e) * 1024 * 512;
;     convT_tile(src, 512, kt * 64, ct * 64, p.WguT + (size_t)(l * 16 + e) * 1024 * 1024, 1024, 0, 1, which, smem);
;     return;
.Lcv_se5:
	v_lshl_add_u32 v116, v98, s94, v102
	v_lshl_add_u32 v117, v99, s94, v102
	v_lshl_add_u32 v118, v100, s94, v102
	v_lshl_add_u32 v119, v101, s94, v102
	global_load_dwordx4 v[54:57], v116, s[88:89] nt
	global_load_dwordx4 v[58:61], v117, s[88:89] nt
	global_load_dwordx4 v[62:65], v118, s[88:89] nt
	global_load_dwordx4 v[66:69], v119, s[88:89] nt
	s_add_i32 s59, s2, 0x600
	s_cmp_lt_u32 s59, 0x1000
	s_cbranch_scc0 .Lcv_dd3
	s_lshr_b32 s60, s59, 11
	s_bfe_u32 s71, s59, 0x40007
	s_bfe_u32 s35, s59, 0x30004
	s_and_b32 s51, s59, 15
	s_lshl_b32 s0, s36, 4
	s_add_i32 s71, s71, s0
	s_lshl_b32 s71, s71, 21
	s_lshl_b32 s35, s35, 7
	s_lshl_b32 s60, s60, 4
	s_add_i32 s35, s35, s60
	s_lshl_b32 s35, s35, 11
	s_add_i32 s71, s71, s35
	s_lshl_b32 s51, s51, 7
	s_add_i32 s71, s71, s51
	s_add_u32 s0, s98, s71
	s_addc_u32 s1, s99, 0
	v_mov_b32_e32 v120, v103
	v_mov_b32_e32 v121, v104
	s_branch .Lcv_de3

; __device__ __forceinline__ u16 f2bf(float f) { return (u16)(pack2(f, 0.f) & 0xffffu); }
; __device__ __forceinline__ void convT_tile(const float* __restrict__ src, int lds, int k0, int c0, u16* __restrict__ dst, int Kd,
;                                            int rbase, int mode, int which, unsigned char* smem, const float* __restrict__ kscale = nullptr) {
;     ...
; #pragma unroll
;   for (int i = 0; i < 4; ++i) {
;     const int kk = i * 16 + (t >> 4), cc = (t & 15) * 4;
;     const float sc = kscale ? kscale[k0 + kk] : 1.f;
;     tile[kk * 65 + cc + 0] = v4[i].x * sc; tile[kk * 65 + cc + 1] = v4[i].y * sc;
;     tile[kk * 65 + cc + 2] = v4[i].z * sc; tile[kk * 65 + cc + 3] = v4[i].w * sc;
;   }
;   __syncthreads();
; #pragma unroll
;   for (int i = 0; i < 16; ++i) {
;     const int cc = i * 4 + (t >> 6), kk = t & 63;
;     int row;
;     if (mode == 0) row = rbase + cc;
;     else { const int f = c0 + cc; row = (((f >> 4) * 2 + which) << 4) + (f & 15); }
;     dst[(size_t)row * Kd + k0 + kk] = f2bf(tile[kk * 65 + cc]);
;   }
;   __syncthreads();
; }
.Lcv_de3:
	s_waitcnt vmcnt(12)
	ds_write2_b32 v111, v132, v133 offset1:1
	ds_write2_b32 v111, v134, v135 offset0:2 offset1:3
	ds_write2_b32 v112, v136, v137 offset1:1
	ds_write2_b32 v112, v138, v139 offset0:2 offset1:3
	ds_write2_b32 v113, v140, v141 offset1:1
	ds_write2_b32 v113, v142, v143 offset0:2 offset1:3
	ds_write2_b32 v114, v144, v145 offset1:1
	ds_write2_b32 v114, v146, v147 offset0:2 offset1:3
	s_waitcnt lgkmcnt(0)
	s_barrier
	ds_read_b32 v72, v115 offset:16640
	ds_read_b32 v73, v115 offset:16900
	ds_read_b32 v74, v115 offset:17160
	ds_read_b32 v75, v115 offset:17420
	ds_read_b32 v76, v115 offset:17680
	ds_read_b32 v77, v115 offset:17940
	ds_read_b32 v78, v115 offset:18200
	ds_read_b32 v79, v115 offset:18460
	ds_read_b32 v26, v115 offset:16768
	ds_read_b32 v27, v115 offset:17028
	ds_read_b32 v28, v115 offset:17288
	ds_read_b32 v29, v115 offset:17548
	ds_read_b32 v30, v115 offset:17808
	ds_read_b32 v31, v115 offset:18068
	ds_read_b32 v32, v115 offset:18328
	ds_read_b32 v33, v115 offset:18588
	s_waitcnt lgkmcnt(8)
	v_cvt_pk_bf16_f32 v124, v72, v73
	v_cvt_pk_bf16_f32 v125, v74, v75
	v_cvt_pk_bf16_f32 v126, v76, v77
	v_cvt_pk_bf16_f32 v127, v78, v79
	global_store_dwordx4 v120, v[124:127], s[0:1]
	s_waitcnt lgkmcnt(0)
	v_cvt_pk_bf16_f32 v128, v26, v27
	v_cvt_pk_bf16_f32 v129, v28, v29
	v_cvt_pk_bf16_f32 v130, v30, v31
	v_cvt_pk_bf16_f32 v131, v32, v33
	global_store_dwordx4 v121, v[128:131], s[0:1]
	s_add_i32 s59, s2, 0xc00
	s_cmp_lt_u32 s59, 0x1000
	s_cbranch_scc0 .Lcv_sd6
	s_lshr_b32 s60, s59, 11
	s_bfe_u32 s71, s59, 0x40007
	s_bfe_u32 s35, s59, 0x30004
	s_and_b32 s51, s59, 15
	s_lshl_b32 s0, s36, 4
	s_add_i32 s71, s71, s0
	s_lshl_b32 s71, s71, 21
	s_lshl_b32 s0, s51, 17
	s_add_i32 s71, s71, s0
	s_lshl_b32 s0, s35, 8
	s_add_i32 s71, s71, s0
	s_cmp_eq_u32 s60, 0
	s_cselect_b32 s88, s52, s54
	s_cselect_b32 s89, s53, s55
	s_add_u32 s88, s88, s71
	s_addc_u32 s89, s89, 0
	s_mov_b32 s94, 11
	s_branch .Lcv_se6

; __device__ __forceinline__ u16 f2bf(float f) { return (u16)(pack2(f, 0.f) & 0xffffu); }
; __device__ __forceinline__ int tid_() { int t = threadIdx.x; asm volatile("" : "+v"(t)); return t; }
; __device__ __forceinline__ void convT_tile(const float* __restrict__ src, int lds, int k0, int c0, u16* __restrict__ dst, int Kd,
;                                            int rbase, int mode, int which, unsigned char* smem, const float* __restrict__ kscale = nullptr) {
;   float* tile = (float*)smem;
;   const int t = tid_();
;   float4 v4[4];
; #pragma unroll
;   for (int i = 0; i < 4; ++i) {
;     const f32x4 w_ = __builtin_nontemporal_load((const f32x4*)(src + (size_t)(k0 + i * 16 + (t >> 4)) * lds + c0 + (t & 15) * 4));
;     v4[i] = make_float4(w_[0], w_[1], w_[2], w_[3]);
;   }
; #pragma unroll
;   for (int i = 0; i < 4; ++i) {
;     const int kk = i * 16 + (t >> 4), cc = (t & 15) * 4;
;     const float sc = kscale ? kscale[k0 + kk] : 1.f;
;     tile[kk * 65 + cc + 0] = v4[i].x * sc; tile[kk * 65 + cc + 1] = v4[i].y * sc;
;     tile[kk * 65 + cc + 2] = v4[i].z * sc; tile[kk * 65 + cc + 3] = v4[i].w * sc;
;   }
;   __syncthreads();
; #pragma unroll
;   for (int i = 0; i < 16; ++i) {
;     const int cc = i * 4 + (t >> 6), kk = t & 63;
;     int row;
;     if (mode == 0) row = rbase + cc;
;     else { const int f = c0 + cc; row = (((f >> 4) * 2 + which) << 4) + (f & 15); }
;     dst[(size_t)row * Kd + k0 + kk] = f2bf(tile[kk * 65 + cc]);
;   }
;   __syncthreads();
; }
; __device__ __forceinline__ void conv_item(const Params& p, int it, unsigned char* smem) {
;     ...
;   if (r < 4096) {
;     const int which = r >> 11, r2 = r & 2047, e = r2 >> 7, r3 = r2 & 127, ct = r3 >> 4, kt = r3 & 15;
;     const float* src = (which ? p.w_up : p.w_gate) + (size_t)(l * 16 + e) * 1024 * 512;
;     convT_tile(src, 512, kt * 64, ct * 64, p.WguT + (size_t)(l * 16 + e) * 1024 * 1024, 1024, 0, 1, which, smem);
;     return;
.Lcv_se6:
	v_lshl_add_u32 v116, v98, s94, v102
	v_lshl_add_u32 v117, v99, s94, v102
	v_lshl_add_u32 v118, v100, s94, v102
	v_lshl_add_u32 v119, v101, s94, v102
	global_load_dwordx4 v[132:135], v116, s[88:89] nt
	global_load_dwordx4 v[136:139], v117, s[88:89] nt
	global_load_dwordx4 v[140:143], v118, s[88:89] nt
	global_load_dwordx4 v[144:147], v119, s[88:89] nt
	s_add_i32 s59, s2, 0x800
	s_cmp_lt_u32 s59, 0x1000
	s_cbranch_scc0 .Lcv_dd4
	s_lshr_b32 s60, s59, 11
	s_bfe_u32 s71, s59, 0x40007
	s_bfe_u32 s35, s59, 0x30004
	s_and_b32 s51, s59, 15
	s_lshl_b32 s0, s36, 4
	s_add_i32 s71, s71, s0
	s_lshl_b32 s71, s71, 21
	s_lshl_b32 s35, s35, 7
	s_lshl_b32 s60, s60, 4
	s_add_i32 s35, s35, s60
	s_lshl_b32 s35, s35, 11
	s_add_i32 s71, s71, s35
	s_lshl_b32 s51, s51, 7
	s_add_i32 s71, s71, s51
	s_add_u32 s0, s98, s71
	s_addc_u32 s1, s99, 0
	v_mov_b32_e32 v120, v103
	v_mov_b32_e32 v121, v104
	s_branch .Lcv_de4

; __device__ __forceinline__ u16 f2bf(float f) { return (u16)(pack2(f, 0.f) & 0xffffu); }
; __device__ __forceinline__ void convT_tile(const float* __restrict__ src, int lds, int k0, int c0, u16* __restrict__ dst, int Kd,
;                                            int rbase, int mode, int which, unsigned char* smem, const float* __restrict__ kscale = nullptr) {
;     ...
; #pragma unroll
;   for (int i = 0; i < 4; ++i) {
;     const int kk = i * 16 + (t >> 4), cc = (t & 15) * 4;
;     const float sc = kscale ? kscale[k0 + kk] : 1.f;
;     tile[kk * 65 + cc + 0] = v4[i].x * sc; tile[kk * 65 + cc + 1] = v4[i].y * sc;
;     tile[kk * 65 + cc + 2] = v4[i].z * sc; tile[kk * 65 + cc + 3] = v4[i].w * sc;
;   }
;   __syncthreads();
; #pragma unroll
;   for (int i = 0; i < 16; ++i) {
;     const int cc = i * 4 + (t >> 6), kk = t & 63;
;     int row;
;     if (mode == 0) row = rbase + cc;
;     else { const int f = c0 + cc; row = (((f >> 4) * 2 + which) << 4) + (f & 15); }
;     dst[(size_t)row * Kd + k0 + kk] = f2bf(tile[kk * 65 + cc]);
;   }
;   __syncthreads();
; }
.Lcv_de4:
	s_waitcnt vmcnt(12)
	ds_write2_b32 v107, v148, v149 offset1:1
	ds_write2_b32 v107, v150, v151 offset0:2 offset1:3
	ds_write2_b32 v108, v152, v153 offset1:1
	ds_write2_b32 v108, v154, v155 offset0:2 offset1:3
	ds_write2_b32 v109, v156, v157 offset1:1
	ds_write2_b32 v109, v158, v159 offset0:2 offset1:3
	ds_write2_b32 v110, v160, v161 offset1:1
	ds_write2_b32 v110, v162, v163 offset0:2 offset1:3
	s_waitcnt lgkmcnt(0)
	s_barrier
	ds_read_b32 v72, v115 offset:0
	ds_read_b32 v73, v115 offset:260
	ds_read_b32 v74, v115 offset:520
	ds_read_b32 v75, v115 offset:780
	ds_read_b32 v76, v115 offset:1040
	ds_read_b32 v77, v115 offset:1300
	ds_read_b32 v78, v115 offset:1560
	ds_read_b32 v79, v115 offset:1820
	ds_read_b32 v26, v115 offset:128
	ds_read_b32 v27, v115 offset:388
	ds_read_b32 v28, v115 offset:648
	ds_read_b32 v29, v115 offset:908
	ds_read_b32 v30, v115 offset:1168
	ds_read_b32 v31, v115 offset:1428
	ds_read_b32 v32, v115 offset:1688
	ds_read_b32 v33, v115 offset:1948
	s_waitcnt lgkmcnt(8)
	v_cvt_pk_bf16_f32 v124, v72, v73
	v_cvt_pk_bf16_f32 v125, v74, v75
	v_cvt_pk_bf16_f32 v126, v76, v77
	v_cvt_pk_bf16_f32 v127, v78, v79
	global_store_dwordx4 v120, v[124:127], s[0:1]
	s_waitcnt lgkmcnt(0)
	v_cvt_pk_bf16_f32 v128, v26, v27
	v_cvt_pk_bf16_f32 v129, v28, v29
	v_cvt_pk_bf16_f32 v130, v30, v31
	v_cvt_pk_bf16_f32 v131, v32, v33
	global_store_dwordx4 v121, v[128:131], s[0:1]
	s_add_i32 s59, s2, 0xe00
	s_cmp_lt_u32 s59, 0x1000
	s_cbranch_scc0 .Lcv_sd7
	s_lshr_b32 s60, s59, 11
	s_bfe_u32 s71, s59, 0x40007
	s_bfe_u32 s35, s59, 0x30004
	s_and_b32 s51, s59, 15
	s_lshl_b32 s0, s36, 4
	s_add_i32 s71, s71, s0
	s_lshl_b32 s71, s71, 21
	s_lshl_b32 s0, s51, 17
	s_add_i32 s71, s71, s0
	s_lshl_b32 s0, s35, 8
	s_add_i32 s71, s71, s0
	s_cmp_eq_u32 s60, 0
	s_cselect_b32 s88, s52, s54
	s_cselect_b32 s89, s53, s55
	s_add_u32 s88, s88, s71
	s_addc_u32 s89, s89, 0
	s_mov_b32 s94, 11
	s_branch .Lcv_se7

; __device__ __forceinline__ u16 f2bf(float f) { return (u16)(pack2(f, 0.f) & 0xffffu); }
; __device__ __forceinline__ int tid_() { int t = threadIdx.x; asm volatile("" : "+v"(t)); return t; }
; __device__ __forceinline__ void convT_tile(const float* __restrict__ src, int lds, int k0, int c0, u16* __restrict__ dst, int Kd,
;                                            int rbase, int mode, int which, unsigned char* smem, const float* __restrict__ kscale = nullptr) {
;   float* tile = (float*)smem;
;   const int t = tid_();
;   float4 v4[4];
; #pragma unroll
;   for (int i = 0; i < 4; ++i) {
;     const f32x4 w_ = __builtin_nontemporal_load((const f32x4*)(src + (size_t)(k0 + i * 16 + (t >> 4)) * lds + c0 + (t & 15) * 4));
;     v4[i] = make_float4(w_[0], w_[1], w_[2], w_[3]);
;   }
; #pragma unroll
;   for (int i = 0; i < 4; ++i) {
;     const int kk = i * 16 + (t >> 4), cc = (t & 15) * 4;
;     const float sc = kscale ? kscale[k0 + kk] : 1.f;
;     tile[kk * 65 + cc + 0] = v4[i].x * sc; tile[kk * 65 + cc + 1] = v4[i].y * sc;
;     tile[kk * 65 + cc + 2] = v4[i].z * sc; tile[kk * 65 + cc + 3] = v4[i].w * sc;
;   }
;   __syncthreads();
; #pragma unroll
;   for (int i = 0; i < 16; ++i) {
;     const int cc = i * 4 + (t >> 6), kk = t & 63;
;     int row;
;     if (mode == 0) row = rbase + cc;
;     else { const int f = c0 + cc; row = (((f >> 4) * 2 + which) << 4) + (f & 15); }
;     dst[(size_t)row * Kd + k0 + kk] = f2bf(tile[kk * 65 + cc]);
;   }
;   __syncthreads();
; }
; __device__ __forceinline__ void conv_item(const Params& p, int it, unsigned char* smem) {
;     ...
;   if (r < 4096) {
;     const int which = r >> 11, r2 = r & 2047, e = r2 >> 7, r3 = r2 & 127, ct = r3 >> 4, kt = r3 & 15;
;     const float* src = (which ? p.w_up : p.w_gate) + (size_t)(l * 16 + e) * 1024 * 512;
;     convT_tile(src, 512, kt * 64, ct * 64, p.WguT + (size_t)(l * 16 + e) * 1024 * 1024, 1024, 0, 1, which, smem);
;     return;
.Lcv_se7:
	v_lshl_add_u32 v116, v98, s94, v102
	v_lshl_add_u32 v117, v99, s94, v102
	v_lshl_add_u32 v118, v100, s94, v102
	v_lshl_add_u32 v119, v101, s94, v102
	global_load_dwordx4 v[148:151], v116, s[88:89] nt
	global_load_dwordx4 v[152:155], v117, s[88:89] nt
	global_load_dwordx4 v[156:159], v118, s[88:89] nt
	global_load_dwordx4 v[160:163], v119, s[88:89] nt
	s_add_i32 s59, s2, 0xa00
	s_cmp_lt_u32 s59, 0x1000
	s_cbranch_scc0 .Lcv_dd5
	s_lshr_b32 s60, s59, 11
	s_bfe_u32 s71, s59, 0x40007
	s_bfe_u32 s35, s59, 0x30004
	s_and_b32 s51, s59, 15
	s_lshl_b32 s0, s36, 4
	s_add_i32 s71, s71, s0
	s_lshl_b32 s71, s71, 21
	s_lshl_b32 s35, s35, 7
	s_lshl_b32 s60, s60, 4
	s_add_i32 s35, s35, s60
	s_lshl_b32 s35, s35, 11
	s_add_i32 s71, s71, s35
	s_lshl_b32 s51, s51, 7
	s_add_i32 s71, s71, s51
	s_add_u32 s0, s98, s71
	s_addc_u32 s1, s99, 0
	v_mov_b32_e32 v120, v103
	v_mov_b32_e32 v121, v104
	s_branch .Lcv_de5

; __device__ __forceinline__ u16 f2bf(float f) { return (u16)(pack2(f, 0.f) & 0xffffu); }
; __device__ __forceinline__ void convT_tile(const float* __restrict__ src, int lds, int k0, int c0, u16* __restrict__ dst, int Kd,
;                                            int rbase, int mode, int which, unsigned char* smem, const float* __restrict__ kscale = nullptr) {
;     ...
; #pragma unroll
;   for (int i = 0; i < 4; ++i) {
;     const int kk = i * 16 + (t >> 4), cc = (t & 15) * 4;
;     const float sc = kscale ? kscale[k0 + kk] : 1.f;
;     tile[kk * 65 + cc + 0] = v4[i].x * sc; tile[kk * 65 + cc + 1] = v4[i].y * sc;
;     tile[kk * 65 + cc + 2] = v4[i].z * sc; tile[kk * 65 + cc + 3] = v4[i].w * sc;
;   }
;   __syncthreads();
; #pragma unroll
;   for (int i = 0; i < 16; ++i) {
;     const int cc = i * 4 + (t >> 6), kk = t & 63;
;     int row;
;     if (mode == 0) row = rbase + cc;
;     else { const int f = c0 + cc; row = (((f >> 4) * 2 + which) << 4) + (f & 15); }
;     dst[(size_t)row * Kd + k0 + kk] = f2bf(tile[kk * 65 + cc]);
;   }
;   __syncthreads();
; }
.Lcv_de5:
	s_waitcnt vmcnt(12)
	ds_write2_b32 v111, v54, v55 offset1:1
	ds_write2_b32 v111, v56, v57 offset0:2 offset1:3
	ds_write2_b32 v112, v58, v59 offset1:1
	ds_write2_b32 v112, v60, v61 offset0:2 offset1:3
	ds_write2_b32 v113, v62, v63 offset1:1
	ds_write2_b32 v113, v64, v65 offset0:2 offset1:3
	ds_write2_b32 v114, v66, v67 offset1:1
	ds_write2_b32 v114, v68, v69 offset0:2 offset1:3
	s_waitcnt lgkmcnt(0)
	s_barrier
	ds_read_b32 v72, v115 offset:16640
	ds_read_b32 v73, v115 offset:16900
	ds_read_b32 v74, v115 offset:17160
	ds_read_b32 v75, v115 offset:17420
	ds_read_b32 v76, v115 offset:17680
	ds_read_b32 v77, v115 offset:17940
	ds_read_b32 v78, v115 offset:18200
	ds_read_b32 v79, v115 offset:18460
	ds_read_b32 v26, v115 offset:16768
	ds_read_b32 v27, v115 offset:17028
	ds_read_b32 v28, v115 offset:17288
	ds_read_b32 v29, v115 offset:17548
	ds_read_b32 v30, v115 offset:17808
	ds_read_b32 v31, v115 offset:18068
	ds_read_b32 v32, v115 offset:18328
	ds_read_b32 v33, v115 offset:18588
	s_waitcnt lgkmcnt(8)
	v_cvt_pk_bf16_f32 v124, v72, v73
	v_cvt_pk_bf16_f32 v125, v74, v75
	v_cvt_pk_bf16_f32 v126, v76, v77
	v_cvt_pk_bf16_f32 v127, v78, v79
	global_store_dwordx4 v120, v[124:127], s[0:1]
	s_waitcnt lgkmcnt(0)
	v_cvt_pk_bf16_f32 v128, v26, v27
	v_cvt_pk_bf16_f32 v129, v28, v29
	v_cvt_pk_bf16_f32 v130, v30, v31
	v_cvt_pk_bf16_f32 v131, v32, v33
	global_store_dwordx4 v121, v[128:131], s[0:1]
	s_add_i32 s59, s2, 0x1000
	s_cmp_lt_u32 s59, 0x1000
	s_cbranch_scc0 .Lcv_sd8
	s_lshr_b32 s60, s59, 11
	s_bfe_u32 s71, s59, 0x40007
	s_bfe_u32 s35, s59, 0x30004
	s_and_b32 s51, s59, 15
	s_lshl_b32 s0, s36, 4
	s_add_i32 s71, s71, s0
	s_lshl_b32 s71, s71, 21
	s_lshl_b32 s0, s51, 17
	s_add_i32 s71, s71, s0
	s_lshl_b32 s0, s35, 8
	s_add_i32 s71, s71, s0
	s_cmp_eq_u32 s60, 0
	s_cselect_b32 s88, s52, s54
	s_cselect_b32 s89, s53, s55
	s_add_u32 s88, s88, s71
	s_addc_u32 s89, s89, 0
	s_mov_b32 s94, 11
	s_branch .Lcv_se8

; __device__ __forceinline__ u16 f2bf(float f) { return (u16)(pack2(f, 0.f) & 0xffffu); }
; __device__ __forceinline__ int tid_() { int t = threadIdx.x; asm volatile("" : "+v"(t)); return t; }
; __device__ __forceinline__ void convT_tile(const float* __restrict__ src, int lds, int k0, int c0, u16* __restrict__ dst, int Kd,
;                                            int rbase, int mode, int which, unsigned char* smem, const float* __restrict__ kscale = nullptr) {
;   float* tile = (float*)smem;
;   const int t = tid_();
;   float4 v4[4];
; #pragma unroll
;   for (int i = 0; i < 4; ++i) {
;     const f32x4 w_ = __builtin_nontemporal_load((const f32x4*)(src + (size_t)(k0 + i * 16 + (t >> 4)) * lds + c0 + (t & 15) * 4));
;     v4[i] = make_float4(w_[0], w_[1], w_[2], w_[3]);
;   }
; #pragma unroll
;   for (int i = 0; i < 4; ++i) {
;     const int kk = i * 16 + (t >> 4), cc = (t & 15) * 4;
;     const float sc = kscale ? kscale[k0 + kk] : 1.f;
;     tile[kk * 65 + cc + 0] = v4[i].x * sc; tile[kk * 65 + cc + 1] = v4[i].y * sc;
;     tile[kk * 65 + cc + 2] = v4[i].z * sc; tile[kk * 65 + cc + 3] = v4[i].w * sc;
;   }
;   __syncthreads();
; #pragma unroll
;   for (int i = 0; i < 16; ++i) {
;     const int cc = i * 4 + (t >> 6), kk = t & 63;
;     int row;
;     if (mode == 0) row = rbase + cc;
;     else { const int f = c0 + cc; row = (((f >> 4) * 2 + which) << 4) + (f & 15); }
;     dst[(size_t)row * Kd + k0 + kk] = f2bf(tile[kk * 65 + cc]);
;   }
;   __syncthreads();
; }
; __device__ __forceinline__ void conv_item(const Params& p, int it, unsigned char* smem) {
;     ...
;   if (r < 4096) {
;     const int which = r >> 11, r2 = r & 2047, e = r2 >> 7, r3 = r2 & 127, ct = r3 >> 4, kt = r3 & 15;
;     const float* src = (which ? p.w_up : p.w_gate) + (size_t)(l * 16 + e) * 1024 * 512;
;     convT_tile(src, 512, kt * 64, ct * 64, p.WguT + (size_t)(l * 16 + e) * 1024 * 1024, 1024, 0, 1, which, smem);
;     return;
.Lcv_se8:
	v_lshl_add_u32 v116, v98, s94, v102
	v_lshl_add_u32 v117, v99, s94, v102
	v_lshl_add_u32 v118, v100, s94, v102
	v_lshl_add_u32 v119, v101, s94, v102
	global_load_dwordx4 v[54:57], v116, s[88:89] nt
	global_load_dwordx4 v[58:61], v117, s[88:89] nt
	global_load_dwordx4 v[62:65], v118, s[88:89] nt
	global_load_dwordx4 v[66:69], v119, s[88:89] nt
	s_add_i32 s59, s2, 0xc00
	s_cmp_lt_u32 s59, 0x1000
	s_cbranch_scc0 .Lcv_dd6
	s_lshr_b32 s60, s59, 11
	s_bfe_u32 s71, s59, 0x40007
	s_bfe_u32 s35, s59, 0x30004
	s_and_b32 s51, s59, 15
	s_lshl_b32 s0, s36, 4
	s_add_i32 s71, s71, s0
	s_lshl_b32 s71, s71, 21
	s_lshl_b32 s35, s35, 7
	s_lshl_b32 s60, s60, 4
	s_add_i32 s35, s35, s60
	s_lshl_b32 s35, s35, 11
	s_add_i32 s71, s71, s35
	s_lshl_b32 s51, s51, 7
	s_add_i32 s71, s71, s51
	s_add_u32 s0, s98, s71
	s_addc_u32 s1, s99, 0
	v_mov_b32_e32 v120, v103
	v_mov_b32_e32 v121, v104
	s_branch .Lcv_de6

; __device__ __forceinline__ u16 f2bf(float f) { return (u16)(pack2(f, 0.f) & 0xffffu); }
; __device__ __forceinline__ void convT_tile(const float* __restrict__ src, int lds, int k0, int c0, u16* __restrict__ dst, int Kd,
;                                            int rbase, int mode, int which, unsigned char* smem, const float* __restrict__ kscale = nullptr) {
;     ...
; #pragma unroll
;   for (int i = 0; i < 4; ++i) {
;     const int kk = i * 16 + (t >> 4), cc = (t & 15) * 4;
;     const float sc = kscale ? kscale[k0 + kk] : 1.f;
;     tile[kk * 65 + cc + 0] = v4[i].x * sc; tile[kk * 65 + cc + 1] = v4[i].y * sc;
;     tile[kk * 65 + cc + 2] = v4[i].z * sc; tile[kk * 65 + cc + 3] = v4[i].w * sc;
;   }
;   __syncthreads();
; #pragma unroll
;   for (int i = 0; i < 16; ++i) {
;     const int cc = i * 4 + (t >> 6), kk = t & 63;
;     int row;
;     if (mode == 0) row = rbase + cc;
;     else { const int f = c0 + cc; row = (((f >> 4) * 2 + which) << 4) + (f & 15); }
;     dst[(size_t)row * Kd + k0 + kk] = f2bf(tile[kk * 65 + cc]);
;   }
;   __syncthreads();
; }
.Lcv_de6:
	s_waitcnt vmcnt(12)
	ds_write2_b32 v107, v132, v133 offset1:1
	ds_write2_b32 v107, v134, v135 offset0:2 offset1:3
	ds_write2_b32 v108, v136, v137 offset1:1
	ds_write2_b32 v108, v138, v139 offset0:2 offset1:3
	ds_write2_b32 v109, v140, v141 offset1:1
	ds_write2_b32 v109, v142, v143 offset0:2 offset1:3
	ds_write2_b32 v110, v144, v145 offset1:1
	ds_write2_b32 v110, v146, v147 offset0:2 offset1:3
	s_waitcnt lgkmcnt(0)
	s_barrier
	ds_read_b32 v72, v115 offset:0
	ds_read_b32 v73, v115 offset:260
	ds_read_b32 v74, v115 offset:520
	ds_read_b32 v75, v115 offset:780
	ds_read_b32 v76, v115 offset:1040
	ds_read_b32 v77, v115 offset:1300
	ds_read_b32 v78, v115 offset:1560
	ds_read_b32 v79, v115 offset:1820
	ds_read_b32 v26, v115 offset:128
	ds_read_b32 v27, v115 offset:388
	ds_read_b32 v28, v115 offset:648
	ds_read_b32 v29, v115 offset:908
	ds_read_b32 v30, v115 offset:1168
	ds_read_b32 v31, v115 offset:1428
	ds_read_b32 v32, v115 offset:1688
	ds_read_b32 v33, v115 offset:1948
	s_waitcnt lgkmcnt(8)
	v_cvt_pk_bf16_f32 v124, v72, v73
	v_cvt_pk_bf16_f32 v125, v74, v75
	v_cvt_pk_bf16_f32 v126, v76, v77
	v_cvt_pk_bf16_f32 v127, v78, v79
	global_store_dwordx4 v120, v[124:127], s[0:1]
	s_waitcnt lgkmcnt(0)
	v_cvt_pk_bf16_f32 v128, v26, v27
	v_cvt_pk_bf16_f32 v129, v28, v29
	v_cvt_pk_bf16_f32 v130, v30, v31
	v_cvt_pk_bf16_f32 v131, v32, v33
	global_store_dwordx4 v121, v[128:131], s[0:1]
	s_add_i32 s59, s2, 0x1200
	s_cmp_lt_u32 s59, 0x1000
	s_cbranch_scc0 .Lcv_sd9
	s_lshr_b32 s60, s59, 11
	s_bfe_u32 s71, s59, 0x40007
	s_bfe_u32 s35, s59, 0x30004
	s_and_b32 s51, s59, 15
	s_lshl_b32 s0, s36, 4
	s_add_i32 s71, s71, s0
	s_lshl_b32 s71, s71, 21
	s_lshl_b32 s0, s51, 17
	s_add_i32 s71, s71, s0
	s_lshl_b32 s0, s35, 8
	s_add_i32 s71, s71, s0
	s_cmp_eq_u32 s60, 0
	s_cselect_b32 s88, s52, s54
	s_cselect_b32 s89, s53, s55
	s_add_u32 s88, s88, s71
	s_addc_u32 s89, s89, 0
	s_mov_b32 s94, 11
	s_branch .Lcv_se9

; __device__ __forceinline__ u16 f2bf(float f) { return (u16)(pack2(f, 0.f) & 0xffffu); }
; __device__ __forceinline__ void convT_tile(const float* __restrict__ src, int lds, int k0, int c0, u16* __restrict__ dst, int Kd,
;                                            int rbase, int mode, int which, unsigned char* smem, const float* __restrict__ kscale = nullptr) {
;     ...
; #pragma unroll
;   for (int i = 0; i < 4; ++i) {
;     const int kk = i * 16 + (t >> 4), cc = (t & 15) * 4;
;     const float sc = kscale ? kscale[k0 + kk] : 1.f;
;     tile[kk * 65 + cc + 0] = v4[i].x * sc; tile[kk * 65 + cc + 1] = v4[i].y * sc;
;     tile[kk * 65 + cc + 2] = v4[i].z * sc; tile[kk * 65 + cc + 3] = v4[i].w * sc;
;   }
;   __syncthreads();
; #pragma unroll
;   for (int i = 0; i < 16; ++i) {
;     const int cc = i * 4 + (t >> 6), kk = t & 63;
;     int row;
;     if (mode == 0) row = rbase + cc;
;     else { const int f = c0 + cc; row = (((f >> 4) * 2 + which) << 4) + (f & 15); }
;     dst[(size_t)row * Kd + k0 + kk] = f2bf(tile[kk * 65 + cc]);
;   }
;   __syncthreads();
; }
.Lcv_de7:
	s_waitcnt vmcnt(12)
	ds_write2_b32 v111, v148, v149 offset1:1
	ds_write2_b32 v111, v150, v151 offset0:2 offset1:3
	ds_write2_b32 v112, v152, v153 offset1:1
	ds_write2_b32 v112, v154, v155 offset0:2 offset1:3
	ds_write2_b32 v113, v156, v157 offset1:1
	ds_write2_b32 v113, v158, v159 offset0:2 offset1:3
	ds_write2_b32 v114, v160, v161 offset1:1
	ds_write2_b32 v114, v162, v163 offset0:2 offset1:3
	s_waitcnt lgkmcnt(0)
	s_barrier
	ds_read_b32 v72, v115 offset:16640
	ds_read_b32 v73, v115 offset:16900
	ds_read_b32 v74, v115 offset:17160
	ds_read_b32 v75, v115 offset:17420
	ds_read_b32 v76, v115 offset:17680
	ds_read_b32 v77, v115 offset:17940
	ds_read_b32 v78, v115 offset:18200
	ds_read_b32 v79, v115 offset:18460
	ds_read_b32 v26, v115 offset:16768
	ds_read_b32 v27, v115 offset:17028
	ds_read_b32 v28, v115 offset:17288
	ds_read_b32 v29, v115 offset:17548
	ds_read_b32 v30, v115 offset:17808
	ds_read_b32 v31, v115 offset:18068
	ds_read_b32 v32, v115 offset:18328
	ds_read_b32 v33, v115 offset:18588
	s_waitcnt lgkmcnt(8)
	v_cvt_pk_bf16_f32 v124, v72, v73
	v_cvt_pk_bf16_f32 v125, v74, v75
	v_cvt_pk_bf16_f32 v126, v76, v77
	v_cvt_pk_bf16_f32 v127, v78, v79
	global_store_dwordx4 v120, v[124:127], s[0:1]
	s_waitcnt lgkmcnt(0)
	v_cvt_pk_bf16_f32 v128, v26, v27
	v_cvt_pk_bf16_f32 v129, v28, v29
	v_cvt_pk_bf16_f32 v130, v30, v31
	v_cvt_pk_bf16_f32 v131, v32, v33
	global_store_dwordx4 v121, v[128:131], s[0:1]
	s_add_i32 s59, s2, 0x1400
	s_cmp_lt_u32 s59, 0x1000
	s_cbranch_scc0 .Lcv_sd10
	s_lshr_b32 s60, s59, 11
	s_bfe_u32 s71, s59, 0x40007
	s_bfe_u32 s35, s59, 0x30004
	s_and_b32 s51, s59, 15
	s_lshl_b32 s0, s36, 4
	s_add_i32 s71, s71, s0
	s_lshl_b32 s71, s71, 21
	s_lshl_b32 s0, s51, 17
	s_add_i32 s71, s71, s0
	s_lshl_b32 s0, s35, 8
	s_add_i32 s71, s71, s0
	s_cmp_eq_u32 s60, 0
	s_cselect_b32 s88, s52, s54
	s_cselect_b32 s89, s53, s55
	s_add_u32 s88, s88, s71
	s_addc_u32 s89, s89, 0
	s_mov_b32 s94, 11
	s_branch .Lcv_se10

; __device__ __forceinline__ u16 f2bf(float f) { return (u16)(pack2(f, 0.f) & 0xffffu); }
; __device__ __forceinline__ void convT_tile(const float* __restrict__ src, int lds, int k0, int c0, u16* __restrict__ dst, int Kd,
;                                            int rbase, int mode, int which, unsigned char* smem, const float* __restrict__ kscale = nullptr) {
;     ...
; #pragma unroll
;   for (int i = 0; i < 4; ++i) {
;     const int kk = i * 16 + (t >> 4), cc = (t & 15) * 4;
;     const float sc = kscale ? kscale[k0 + kk] : 1.f;
;     tile[kk * 65 + cc + 0] = v4[i].x * sc; tile[kk * 65 + cc + 1] = v4[i].y * sc;
;     tile[kk * 65 + cc + 2] = v4[i].z * sc; tile[kk * 65 + cc + 3] = v4[i].w * sc;
;   }
;   __syncthreads();
; #pragma unroll
;   for (int i = 0; i < 16; ++i) {
;     const int cc = i * 4 + (t >> 6), kk = t & 63;
;     int row;
;     if (mode == 0) row = rbase + cc;
;     else { const int f = c0 + cc; row = (((f >> 4) * 2 + which) << 4) + (f & 15); }
;     dst[(size_t)row * Kd + k0 + kk] = f2bf(tile[kk * 65 + cc]);
;   }
;   __syncthreads();
; }
.Lcv_de8:
	s_waitcnt vmcnt(12)
	ds_write2_b32 v107, v54, v55 offset1:1
	ds_write2_b32 v107, v56, v57 offset0:2 offset1:3
	ds_write2_b32 v108, v58, v59 offset1:1
	ds_write2_b32 v108, v60, v61 offset0:2 offset1:3
	ds_write2_b32 v109, v62, v63 offset1:1
	ds_write2_b32 v109, v64, v65 offset0:2 offset1:3
	ds_write2_b32 v110, v66, v67 offset1:1
	ds_write2_b32 v110, v68, v69 offset0:2 offset1:3
	s_waitcnt lgkmcnt(0)
	s_barrier
	ds_read_b32 v72, v115 offset:0
	ds_read_b32 v73, v115 offset:260
	ds_read_b32 v74, v115 offset:520
	ds_read_b32 v75, v115 offset:780
	ds_read_b32 v76, v115 offset:1040
	ds_read_b32 v77, v115 offset:1300
	ds_read_b32 v78, v115 offset:1560
	ds_read_b32 v79, v115 offset:1820
	ds_read_b32 v26, v115 offset:128
	ds_read_b32 v27, v115 offset:388
	ds_read_b32 v28, v115 offset:648
	ds_read_b32 v29, v115 offset:908
	ds_read_b32 v30, v115 offset:1168
	ds_read_b32 v31, v115 offset:1428
	ds_read_b32 v32, v115 offset:1688
	ds_read_b32 v33, v115 offset:1948
	s_waitcnt lgkmcnt(8)
	v_cvt_pk_bf16_f32 v124, v72, v73
	v_cvt_pk_bf16_f32 v125, v74, v75
	v_cvt_pk_bf16_f32 v126, v76, v77
	v_cvt_pk_bf16_f32 v127, v78, v79
	global_store_dwordx4 v120, v[124:127], s[0:1]
	s_waitcnt lgkmcnt(0)
	v_cvt_pk_bf16_f32 v128, v26, v27
	v_cvt_pk_bf16_f32 v129, v28, v29
	v_cvt_pk_bf16_f32 v130, v30, v31
	v_cvt_pk_bf16_f32 v131, v32, v33
	global_store_dwordx4 v121, v[128:131], s[0:1]
	s_add_i32 s59, s2, 0x1600
	s_cmp_lt_u32 s59, 0x1000
	s_cbranch_scc0 .Lcv_sd11
	s_lshr_b32 s60, s59, 11
	s_bfe_u32 s71, s59, 0x40007
	s_bfe_u32 s35, s59, 0x30004
	s_and_b32 s51, s59, 15
	s_lshl_b32 s0, s36, 4
	s_add_i32 s71, s71, s0
	s_lshl_b32 s71, s71, 21
	s_lshl_b32 s0, s51, 17
	s_add_i32 s71, s71, s0
	s_lshl_b32 s0, s35, 8
	s_add_i32 s71, s71, s0
	s_cmp_eq_u32 s60, 0
	s_cselect_b32 s88, s52, s54
	s_cselect_b32 s89, s53, s55
	s_add_u32 s88, s88, s71
	s_addc_u32 s89, s89, 0
	s_mov_b32 s94, 11
	s_branch .Lcv_se11

; __device__ __forceinline__ u16 f2bf(float f) { return (u16)(pack2(f, 0.f) & 0xffffu); }
; __device__ __forceinline__ int tid_() { int t = threadIdx.x; asm volatile("" : "+v"(t)); return t; }
; __device__ __forceinline__ void convT_tile(const float* __restrict__ src, int lds, int k0, int c0, u16* __restrict__ dst, int Kd,
;                                            int rbase, int mode, int which, unsigned char* smem, const float* __restrict__ kscale = nullptr) {
;   float* tile = (float*)smem;
;   const int t = tid_();
;   float4 v4[4];
; #pragma unroll
;   for (int i = 0; i < 4; ++i) {
;     const f32x4 w_ = __builtin_nontemporal_load((const f32x4*)(src + (size_t)(k0 + i * 16 + (t >> 4)) * lds + c0 + (t & 15) * 4));
;     v4[i] = make_float4(w_[0], w_[1], w_[2], w_[3]);
;   }
; #pragma unroll
;   for (int i = 0; i < 4; ++i) {
;     const int kk = i * 16 + (t >> 4), cc = (t & 15) * 4;
;     const float sc = kscale ? kscale[k0 + kk] : 1.f;
;     tile[kk * 65 + cc + 0] = v4[i].x * sc; tile[kk * 65 + cc + 1] = v4[i].y * sc;
;     tile[kk * 65 + cc + 2] = v4[i].z * sc; tile[kk * 65 + cc + 3] = v4[i].w * sc;
;   }
;   __syncthreads();
; #pragma unroll
;   for (int i = 0; i < 16; ++i) {
;     const int cc = i * 4 + (t >> 6), kk = t & 63;
;     int row;
;     if (mode == 0) row = rbase + cc;
;     else { const int f = c0 + cc; row = (((f >> 4) * 2 + which) << 4) + (f & 15); }
;     dst[(size_t)row * Kd + k0 + kk] = f2bf(tile[kk * 65 + cc]);
;   }
;   __syncthreads();
; }
; __device__ __forceinline__ void conv_item(const Params& p, int it, unsigned char* smem) {
;     ...
;   if (r < 4096) {
;     const int which = r >> 11, r2 = r & 2047, e = r2 >> 7, r3 = r2 & 127, ct = r3 >> 4, kt = r3 & 15;
;     const float* src = (which ? p.w_up : p.w_gate) + (size_t)(l * 16 + e) * 1024 * 512;
;     convT_tile(src, 512, kt * 64, ct * 64, p.WguT + (size_t)(l * 16 + e) * 1024 * 1024, 1024, 0, 1, which, smem);
;     return;
.Lcv_se11:
	v_lshl_add_u32 v116, v98, s94, v102
	v_lshl_add_u32 v117, v99, s94, v102
	v_lshl_add_u32 v118, v100, s94, v102
	v_lshl_add_u32 v119, v101, s94, v102
	global_load_dwordx4 v[54:57], v116, s[88:89] nt
	global_load_dwordx4 v[58:61], v117, s[88:89] nt
	global_load_dwordx4 v[62:65], v118, s[88:89] nt
	global_load_dwordx4 v[66:69], v119, s[88:89] nt
	s_add_i32 s59, s2, 0x1200
	s_cmp_lt_u32 s59, 0x1000
	s_cbranch_scc0 .Lcv_dd9
	s_lshr_b32 s60, s59, 11
	s_bfe_u32 s71, s59, 0x40007
	s_bfe_u32 s35, s59, 0x30004
	s_and_b32 s51, s59, 15
	s_lshl_b32 s0, s36, 4
	s_add_i32 s71, s71, s0
	s_lshl_b32 s71, s71, 21
	s_lshl_b32 s35, s35, 7
	s_lshl_b32 s60, s60, 4
	s_add_i32 s35, s35, s60
	s_lshl_b32 s35, s35, 11
	s_add_i32 s71, s71, s35
	s_lshl_b32 s51, s51, 7
	s_add_i32 s71, s71, s51
	s_add_u32 s0, s98, s71
	s_addc_u32 s1, s99, 0
	v_mov_b32_e32 v120, v103
	v_mov_b32_e32 v121, v104
	s_branch .Lcv_de9

; __device__ __forceinline__ u16 f2bf(float f) { return (u16)(pack2(f, 0.f) & 0xffffu); }
; __device__ __forceinline__ void convT_tile(const float* __restrict__ src, int lds, int k0, int c0, u16* __restrict__ dst, int Kd,
;                                            int rbase, int mode, int which, unsigned char* smem, const float* __restrict__ kscale = nullptr) {
;     ...
; #pragma unroll
;   for (int i = 0; i < 4; ++i) {
;     const int kk = i * 16 + (t >> 4), cc = (t & 15) * 4;
;     const float sc = kscale ? kscale[k0 + kk] : 1.f;
;     tile[kk * 65 + cc + 0] = v4[i].x * sc; tile[kk * 65 + cc + 1] = v4[i].y * sc;
;     tile[kk * 65 + cc + 2] = v4[i].z * sc; tile[kk * 65 + cc + 3] = v4[i].w * sc;
;   }
;   __syncthreads();
; #pragma unroll
;   for (int i = 0; i < 16; ++i) {
;     const int cc = i * 4 + (t >> 6), kk = t & 63;
;     int row;
;     if (mode == 0) row = rbase + cc;
;     else { const int f = c0 + cc; row = (((f >> 4) * 2 + which) << 4) + (f & 15); }
;     dst[(size_t)row * Kd + k0 + kk] = f2bf(tile[kk * 65 + cc]);
;   }
;   __syncthreads();
; }
.Lcv_de9:
	s_waitcnt vmcnt(12)
	ds_write2_b32 v111, v132, v133 offset1:1
	ds_write2_b32 v111, v134, v135 offset0:2 offset1:3
	ds_write2_b32 v112, v136, v137 offset1:1
	ds_write2_b32 v112, v138, v139 offset0:2 offset1:3
	ds_write2_b32 v113, v140, v141 offset1:1
	ds_write2_b32 v113, v142, v143 offset0:2 offset1:3
	ds_write2_b32 v114, v144, v145 offset1:1
	ds_write2_b32 v114, v146, v147 offset0:2 offset1:3
	s_waitcnt lgkmcnt(0)
	s_barrier
	ds_read_b32 v72, v115 offset:16640
	ds_read_b32 v73, v115 offset:16900
	ds_read_b32 v74, v115 offset:17160
	ds_read_b32 v75, v115 offset:17420
	ds_read_b32 v76, v115 offset:17680
	ds_read_b32 v77, v115 offset:17940
	ds_read_b32 v78, v115 offset:18200
	ds_read_b32 v79, v115 offset:18460
	ds_read_b32 v26, v115 offset:16768
	ds_read_b32 v27, v115 offset:17028
	ds_read_b32 v28, v115 offset:17288
	ds_read_b32 v29, v115 offset:17548
	ds_read_b32 v30, v115 offset:17808
	ds_read_b32 v31, v115 offset:18068
	ds_read_b32 v32, v115 offset:18328
	ds_read_b32 v33, v115 offset:18588
	s_waitcnt lgkmcnt(8)
	v_cvt_pk_bf16_f32 v124, v72, v73
	v_cvt_pk_bf16_f32 v125, v74, v75
	v_cvt_pk_bf16_f32 v126, v76, v77
	v_cvt_pk_bf16_f32 v127, v78, v79
	global_store_dwordx4 v120, v[124:127], s[0:1]
	s_waitcnt lgkmcnt(0)
	v_cvt_pk_bf16_f32 v128, v26, v27
	v_cvt_pk_bf16_f32 v129, v28, v29
	v_cvt_pk_bf16_f32 v130, v30, v31
	v_cvt_pk_bf16_f32 v131, v32, v33
	global_store_dwordx4 v121, v[128:131], s[0:1]
	s_cmp_lt_i32 s34, 0
	s_cbranch_scc1 .Lcv_nol12
	s_mov_b32 s59, s34
	s_cmp_lt_u32 s59, 0x1000
	s_cbranch_scc0 .Lcv_sd12
	s_lshr_b32 s60, s59, 11
	s_bfe_u32 s71, s59, 0x40007
	s_bfe_u32 s35, s59, 0x30004
	s_and_b32 s51, s59, 15
	s_lshl_b32 s0, s36, 4
	s_add_i32 s71, s71, s0
	s_lshl_b32 s71, s71, 21
	s_lshl_b32 s0, s51, 17
	s_add_i32 s71, s71, s0
	s_lshl_b32 s0, s35, 8
	s_add_i32 s71, s71, s0
	s_cmp_eq_u32 s60, 0
	s_cselect_b32 s88, s52, s54
	s_cselect_b32 s89, s53, s55
	s_add_u32 s88, s88, s71
	s_addc_u32 s89, s89, 0
	s_mov_b32 s94, 11
	s_branch .Lcv_se12

; __device__ __forceinline__ void conv_item(const Params& p, int it, unsigned char* smem) {
;     ...
;   if (r < 4096) {
;     const int which = r >> 11, r2 = r & 2047, e = r2 >> 7, r3 = r2 & 127, ct = r3 >> 4, kt = r3 & 15;
;     const float* src = (which ? p.w_up : p.w_gate) + (size_t)(l * 16 + e) * 1024 * 512;
;     convT_tile(src, 512, kt * 64, ct * 64, p.WguT + (size_t)(l * 16 + e) * 1024 * 1024, 1024, 0, 1, which, smem);
;     return;
.Lcv_nol12:
	s_add_i32 s59, s2, 0x1400
	s_cmp_lt_u32 s59, 0x1000
	s_cbranch_scc0 .Lcv_dd10
	s_lshr_b32 s60, s59, 11
	s_bfe_u32 s71, s59, 0x40007
	s_bfe_u32 s35, s59, 0x30004
	s_and_b32 s51, s59, 15
	s_lshl_b32 s0, s36, 4
	s_add_i32 s71, s71, s0
	s_lshl_b32 s71, s71, 21
	s_lshl_b32 s35, s35, 7
	s_lshl_b32 s60, s60, 4
	s_add_i32 s35, s35, s60
	s_lshl_b32 s35, s35, 11
	s_add_i32 s71, s71, s35
	s_lshl_b32 s51, s51, 7
	s_add_i32 s71, s71, s51
	s_add_u32 s0, s98, s71
	s_addc_u32 s1, s99, 0
	v_mov_b32_e32 v120, v103
	v_mov_b32_e32 v121, v104
	s_branch .Lcv_de10

; __device__ __forceinline__ u16 f2bf(float f) { return (u16)(pack2(f, 0.f) & 0xffffu); }
; __device__ __forceinline__ void convT_tile(const float* __restrict__ src, int lds, int k0, int c0, u16* __restrict__ dst, int Kd,
;                                            int rbase, int mode, int which, unsigned char* smem, const float* __restrict__ kscale = nullptr) {
;     ...
; #pragma unroll
;   for (int i = 0; i < 4; ++i) {
;     const int kk = i * 16 + (t >> 4), cc = (t & 15) * 4;
;     const float sc = kscale ? kscale[k0 + kk] : 1.f;
;     tile[kk * 65 + cc + 0] = v4[i].x * sc; tile[kk * 65 + cc + 1] = v4[i].y * sc;
;     tile[kk * 65 + cc + 2] = v4[i].z * sc; tile[kk * 65 + cc + 3] = v4[i].w * sc;
;   }
;   __syncthreads();
; #pragma unroll
;   for (int i = 0; i < 16; ++i) {
;     const int cc = i * 4 + (t >> 6), kk = t & 63;
;     int row;
;     if (mode == 0) row = rbase + cc;
;     else { const int f = c0 + cc; row = (((f >> 4) * 2 + which) << 4) + (f & 15); }
;     dst[(size_t)row * Kd + k0 + kk] = f2bf(tile[kk * 65 + cc]);
;   }
;   __syncthreads();
; }
.Lcv_de10:
	s_cmp_lt_i32 s34, 0
	s_cbranch_scc1 .Lcv_w10
	s_waitcnt vmcnt(12)
	s_branch .Lcv_w10b
.Lcv_w10:
	s_waitcnt vmcnt(8)
.Lcv_w10b:
	ds_write2_b32 v107, v148, v149 offset1:1
	ds_write2_b32 v107, v150, v151 offset0:2 offset1:3
	ds_write2_b32 v108, v152, v153 offset1:1
	ds_write2_b32 v108, v154, v155 offset0:2 offset1:3
	ds_write2_b32 v109, v156, v157 offset1:1
	ds_write2_b32 v109, v158, v159 offset0:2 offset1:3
	ds_write2_b32 v110, v160, v161 offset1:1
	ds_write2_b32 v110, v162, v163 offset0:2 offset1:3
	s_waitcnt lgkmcnt(0)
	s_barrier
	ds_read_b32 v72, v115 offset:0
	ds_read_b32 v73, v115 offset:260
	ds_read_b32 v74, v115 offset:520
	ds_read_b32 v75, v115 offset:780
	ds_read_b32 v76, v115 offset:1040
	ds_read_b32 v77, v115 offset:1300
	ds_read_b32 v78, v115 offset:1560
	ds_read_b32 v79, v115 offset:1820
	ds_read_b32 v26, v115 offset:128
	ds_read_b32 v27, v115 offset:388
	ds_read_b32 v28, v115 offset:648
	ds_read_b32 v29, v115 offset:908
	ds_read_b32 v30, v115 offset:1168
	ds_read_b32 v31, v115 offset:1428
	ds_read_b32 v32, v115 offset:1688
	ds_read_b32 v33, v115 offset:1948
	s_waitcnt lgkmcnt(8)
	v_cvt_pk_bf16_f32 v124, v72, v73
	v_cvt_pk_bf16_f32 v125, v74, v75
	v_cvt_pk_bf16_f32 v126, v76, v77
	v_cvt_pk_bf16_f32 v127, v78, v79
	global_store_dwordx4 v120, v[124:127], s[0:1]
	s_waitcnt lgkmcnt(0)
	v_cvt_pk_bf16_f32 v128, v26, v27
	v_cvt_pk_bf16_f32 v129, v28, v29
	v_cvt_pk_bf16_f32 v130, v30, v31
	v_cvt_pk_bf16_f32 v131, v32, v33
	global_store_dwordx4 v121, v[128:131], s[0:1]
	s_add_i32 s59, s2, 0x1600
	s_cmp_lt_u32 s59, 0x1000
	s_cbranch_scc0 .Lcv_dd11
	s_lshr_b32 s60, s59, 11
	s_bfe_u32 s71, s59, 0x40007
	s_bfe_u32 s35, s59, 0x30004
	s_and_b32 s51, s59, 15
	s_lshl_b32 s0, s36, 4
	s_add_i32 s71, s71, s0
	s_lshl_b32 s71, s71, 21
	s_lshl_b32 s35, s35, 7
	s_lshl_b32 s60, s60, 4
	s_add_i32 s35, s35, s60
	s_lshl_b32 s35, s35, 11
	s_add_i32 s71, s71, s35
	s_lshl_b32 s51, s51, 7
	s_add_i32 s71, s71, s51
	s_add_u32 s0, s98, s71
	s_addc_u32 s1, s99, 0
	v_mov_b32_e32 v120, v103
	v_mov_b32_e32 v121, v104
	s_branch .Lcv_de11

; __device__ __forceinline__ u16 f2bf(float f) { return (u16)(pack2(f, 0.f) & 0xffffu); }
; __device__ __forceinline__ void convT_tile(const float* __restrict__ src, int lds, int k0, int c0, u16* __restrict__ dst, int Kd,
;                                            int rbase, int mode, int which, unsigned char* smem, const float* __restrict__ kscale = nullptr) {
;     ...
; #pragma unroll
;   for (int i = 0; i < 4; ++i) {
;     const int kk = i * 16 + (t >> 4), cc = (t & 15) * 4;
;     const float sc = kscale ? kscale[k0 + kk] : 1.f;
;     tile[kk * 65 + cc + 0] = v4[i].x * sc; tile[kk * 65 + cc + 1] = v4[i].y * sc;
;     tile[kk * 65 + cc + 2] = v4[i].z * sc; tile[kk * 65 + cc + 3] = v4[i].w * sc;
;   }
;   __syncthreads();
; #pragma unroll
;   for (int i = 0; i < 16; ++i) {
;     const int cc = i * 4 + (t >> 6), kk = t & 63;
;     int row;
;     if (mode == 0) row = rbase + cc;
;     else { const int f = c0 + cc; row = (((f >> 4) * 2 + which) << 4) + (f & 15); }
;     dst[(size_t)row * Kd + k0 + kk] = f2bf(tile[kk * 65 + cc]);
;   }
;   __syncthreads();
; }
.Lcv_de11:
	s_cmp_lt_i32 s34, 0
	s_cbranch_scc1 .Lcv_w11
	s_waitcnt vmcnt(8)
	s_branch .Lcv_w11b

; __device__ __forceinline__ u16 f2bf(float f) { return (u16)(pack2(f, 0.f) & 0xffffu); }
; __device__ __forceinline__ void convT_tile(const float* __restrict__ src, int lds, int k0, int c0, u16* __restrict__ dst, int Kd,
;                                            int rbase, int mode, int which, unsigned char* smem, const float* __restrict__ kscale = nullptr) {
;     ...
; #pragma unroll
;   for (int i = 0; i < 4; ++i) {
;     const int kk = i * 16 + (t >> 4), cc = (t & 15) * 4;
;     const float sc = kscale ? kscale[k0 + kk] : 1.f;
;     tile[kk * 65 + cc + 0] = v4[i].x * sc; tile[kk * 65 + cc + 1] = v4[i].y * sc;
;     tile[kk * 65 + cc + 2] = v4[i].z * sc; tile[kk * 65 + cc + 3] = v4[i].w * sc;
;   }
;   __syncthreads();
; #pragma unroll
;   for (int i = 0; i < 16; ++i) {
;     const int cc = i * 4 + (t >> 6), kk = t & 63;
;     int row;
;     if (mode == 0) row = rbase + cc;
;     else { const int f = c0 + cc; row = (((f >> 4) * 2 + which) << 4) + (f & 15); }
;     dst[(size_t)row * Kd + k0 + kk] = f2bf(tile[kk * 65 + cc]);
;   }
;   __syncthreads();
; }
.Lcv_w11b:
	ds_write2_b32 v111, v54, v55 offset1:1
	ds_write2_b32 v111, v56, v57 offset0:2 offset1:3
	ds_write2_b32 v112, v58, v59 offset1:1
	ds_write2_b32 v112, v60, v61 offset0:2 offset1:3
	ds_write2_b32 v113, v62, v63 offset1:1
	ds_write2_b32 v113, v64, v65 offset0:2 offset1:3
	ds_write2_b32 v114, v66, v67 offset1:1
	ds_write2_b32 v114, v68, v69 offset0:2 offset1:3
	s_waitcnt lgkmcnt(0)
	s_barrier
	ds_read_b32 v72, v115 offset:16640
	ds_read_b32 v73, v115 offset:16900
	ds_read_b32 v74, v115 offset:17160
	ds_read_b32 v75, v115 offset:17420
	ds_read_b32 v76, v115 offset:17680
	ds_read_b32 v77, v115 offset:17940
	ds_read_b32 v78, v115 offset:18200
	ds_read_b32 v79, v115 offset:18460
	ds_read_b32 v26, v115 offset:16768
	ds_read_b32 v27, v115 offset:17028
	ds_read_b32 v28, v115 offset:17288
	ds_read_b32 v29, v115 offset:17548
	ds_read_b32 v30, v115 offset:17808
	ds_read_b32 v31, v115 offset:18068
	ds_read_b32 v32, v115 offset:18328
	ds_read_b32 v33, v115 offset:18588
	s_waitcnt lgkmcnt(8)
	v_cvt_pk_bf16_f32 v124, v72, v73
	v_cvt_pk_bf16_f32 v125, v74, v75
	v_cvt_pk_bf16_f32 v126, v76, v77
	v_cvt_pk_bf16_f32 v127, v78, v79
	global_store_dwordx4 v120, v[124:127], s[0:1]
	s_waitcnt lgkmcnt(0)
	v_cvt_pk_bf16_f32 v128, v26, v27
	v_cvt_pk_bf16_f32 v129, v28, v29
	v_cvt_pk_bf16_f32 v130, v30, v31
	v_cvt_pk_bf16_f32 v131, v32, v33
	global_store_dwordx4 v121, v[128:131], s[0:1]
	s_cmp_lt_i32 s34, 0
	s_cbranch_scc1 .Lcv_exit
	s_mov_b32 s59, s34
	s_cmp_lt_u32 s59, 0x1000
	s_cbranch_scc0 .Lcv_dd12
	s_lshr_b32 s60, s59, 11
	s_bfe_u32 s71, s59, 0x40007
	s_bfe_u32 s35, s59, 0x30004
	s_and_b32 s51, s59, 15
	s_lshl_b32 s0, s36, 4
	s_add_i32 s71, s71, s0
	s_lshl_b32 s71, s71, 21
	s_lshl_b32 s35, s35, 7
	s_lshl_b32 s60, s60, 4
	s_add_i32 s35, s35, s60
	s_lshl_b32 s35, s35, 11
	s_add_i32 s71, s71, s35
	s_lshl_b32 s51, s51, 7
	s_add_i32 s71, s71, s51
	s_add_u32 s0, s98, s71
	s_addc_u32 s1, s99, 0
	v_mov_b32_e32 v120, v103
	v_mov_b32_e32 v121, v104
	s_branch .Lcv_de12

; __device__ __forceinline__ u16 f2bf(float f) { return (u16)(pack2(f, 0.f) & 0xffffu); }
; __device__ __forceinline__ void convT_tile(const float* __restrict__ src, int lds, int k0, int c0, u16* __restrict__ dst, int Kd,
;                                            int rbase, int mode, int which, unsigned char* smem, const float* __restrict__ kscale = nullptr) {
;     ...
; #pragma unroll
;   for (int i = 0; i < 4; ++i) {
;     const int kk = i * 16 + (t >> 4), cc = (t & 15) * 4;
;     const float sc = kscale ? kscale[k0 + kk] : 1.f;
;     tile[kk * 65 + cc + 0] = v4[i].x * sc; tile[kk * 65 + cc + 1] = v4[i].y * sc;
;     tile[kk * 65 + cc + 2] = v4[i].z * sc; tile[kk * 65 + cc + 3] = v4[i].w * sc;
;   }
;   __syncthreads();
; #pragma unroll
;   for (int i = 0; i < 16; ++i) {
;     const int cc = i * 4 + (t >> 6), kk = t & 63;
;     int row;
;     if (mode == 0) row = rbase + cc;
;     else { const int f = c0 + cc; row = (((f >> 4) * 2 + which) << 4) + (f & 15); }
;     dst[(size_t)row * Kd + k0 + kk] = f2bf(tile[kk * 65 + cc]);
;   }
;   __syncthreads();
; }
.Lcv_de12:
	s_waitcnt vmcnt(4)
	ds_write2_b32 v107, v132, v133 offset1:1
	ds_write2_b32 v107, v134, v135 offset0:2 offset1:3
	ds_write2_b32 v108, v136, v137 offset1:1
	ds_write2_b32 v108, v138, v139 offset0:2 offset1:3
	ds_write2_b32 v109, v140, v141 offset1:1
	ds_write2_b32 v109, v142, v143 offset0:2 offset1:3
	ds_write2_b32 v110, v144, v145 offset1:1
	ds_write2_b32 v110, v146, v147 offset0:2 offset1:3
	s_waitcnt lgkmcnt(0)
	s_barrier
	ds_read_b32 v72, v115 offset:0
	ds_read_b32 v73, v115 offset:260
	ds_read_b32 v74, v115 offset:520
	ds_read_b32 v75, v115 offset:780
	ds_read_b32 v76, v115 offset:1040
	ds_read_b32 v77, v115 offset:1300
	ds_read_b32 v78, v115 offset:1560
	ds_read_b32 v79, v115 offset:1820
	ds_read_b32 v26, v115 offset:128
	ds_read_b32 v27, v115 offset:388
	ds_read_b32 v28, v115 offset:648
	ds_read_b32 v29, v115 offset:908
	ds_read_b32 v30, v115 offset:1168
	ds_read_b32 v31, v115 offset:1428
	ds_read_b32 v32, v115 offset:1688
	ds_read_b32 v33, v115 offset:1948
	s_waitcnt lgkmcnt(8)
	v_cvt_pk_bf16_f32 v124, v72, v73
	v_cvt_pk_bf16_f32 v125, v74, v75
	v_cvt_pk_bf16_f32 v126, v76, v77
	v_cvt_pk_bf16_f32 v127, v78, v79
	global_store_dwordx4 v120, v[124:127], s[0:1]
	s_waitcnt lgkmcnt(0)
	v_cvt_pk_bf16_f32 v128, v26, v27
	v_cvt_pk_bf16_f32 v129, v28, v29
	v_cvt_pk_bf16_f32 v130, v30, v31
	v_cvt_pk_bf16_f32 v131, v32, v33
	global_store_dwordx4 v121, v[128:131], s[0:1]
.Lcv_exit:
	s_waitcnt vmcnt(0) lgkmcnt(0)
	s_barrier
	s_cmp_eq_u32 s32, 0
	s_cbranch_scc1 .Lcv_ret_pre
	s_branch .Lcv_ret_post
